# SB unit: gate rows loaded before the key loop; the queue claim is waited at the end of the epilogue instead of at its barrier
# speedup vs baseline: 1.0091x; 1.0003x over previous
.LBB0_379:
	s_waitcnt vmcnt(0)
	v_mbcnt_lo_u32_b32 v34, -1, 0
	v_mbcnt_hi_u32_b32 v34, -1, v34
	v_readlane_b32 s98, v255, 38
	v_readlane_b32 s56, v255, 34
	v_readlane_b32 s70, v255, 47
	v_readlane_b32 s78, v255, 36
	v_readlane_b32 s86, v255, 45
	v_sub_u32_e32 v34, 0, v34
	v_readlane_b32 s4, v254, 2
	v_readlane_b32 s72, v255, 32
	v_readlane_b32 s73, v255, 33
	v_readlane_b32 s99, v255, 39
	v_readlane_b32 s57, v255, 35
	s_mov_b32 s68, s95
	v_readlane_b32 s71, v255, 48
	v_readlane_b32 s79, v255, 37
	v_readlane_b32 s30, v255, 40
	v_readlane_b32 s31, v255, 41
	v_readlane_b32 s34, v255, 42
	v_readlane_b32 s87, v255, 46
	s_mov_b64 s[88:89], 0x80
	v_cmp_eq_u32_e32 vcc, s4, v34
	v_mov_b32_e32 v95, 0xf0000
	s_and_saveexec_b64 s[4:5], vcc
	s_cbranch_execz .LBB0_384
	v_mov_b32_e32 v34, s69
	ds_read_b32 v34, v34
	v_readlane_b32 s7, v254, 32
	v_readlane_b32 s8, v254, 34
	v_mov_b32_e32 v95, 0xf0000
	s_waitcnt lgkmcnt(0)
	v_readfirstlane_b32 s6, v34
	s_and_b32 s7, s6, s7
	s_cmp_eq_u32 s7, 0
	v_readlane_b32 s7, v254, 31
	s_cselect_b32 s7, s7, 15
	s_and_b32 s8, s6, s8
	s_cmp_eq_u32 s8, 0
	v_readlane_b32 s8, v254, 33
	s_cselect_b32 s7, s8, s7
	v_readlane_b32 s8, v254, 36
	s_and_b32 s8, s6, s8
	s_cmp_eq_u32 s8, 0
	v_readlane_b32 s8, v254, 35
	s_cselect_b32 s7, s8, s7
	v_readlane_b32 s8, v254, 38
	s_and_b32 s8, s6, s8
	s_cmp_eq_u32 s8, 0
	v_readlane_b32 s8, v254, 37
	s_cselect_b32 s7, s8, s7
	v_readlane_b32 s8, v254, 40
	s_and_b32 s8, s6, s8
	s_cmp_eq_u32 s8, 0
	v_readlane_b32 s8, v254, 39
	s_cselect_b32 s7, s8, s7
	v_readlane_b32 s8, v254, 42
	s_and_b32 s8, s6, s8
	s_cmp_eq_u32 s8, 0
	v_readlane_b32 s8, v254, 41
	s_cselect_b32 s7, s8, s7
	v_readlane_b32 s8, v254, 44
	s_and_b32 s8, s6, s8
	s_cmp_eq_u32 s8, 0
	v_readlane_b32 s8, v254, 43
	s_cselect_b32 s7, s8, s7
	v_readlane_b32 s8, v254, 46
	s_and_b32 s8, s6, s8
	s_cmp_eq_u32 s8, 0
	v_readlane_b32 s8, v254, 45
	s_cselect_b32 s7, s8, s7
	s_bitcmp0_b32 s6, 8
	s_cselect_b32 s6, 8, 15
	s_cmp_eq_u32 s7, 15
	s_cselect_b32 s10, s6, s7
	s_cmp_eq_u32 s10, 15
	s_cbranch_scc1 .LBB0_384
	s_mov_b64 s[8:9], exec
	v_mbcnt_lo_u32_b32 v34, s8, 0
	v_mbcnt_hi_u32_b32 v34, s9, v34
	v_cmp_eq_u32_e32 vcc, 0, v34
	s_and_saveexec_b64 s[6:7], vcc
	s_cbranch_execz .LBB0_383
	s_lshl_b32 s11, s10, 6
	s_add_i32 s11, s11, 64
	s_cmp_lt_u32 s10, 8
	s_cselect_b32 s80, s11, 0
	s_lshl_b64 s[12:13], s[80:81], 2
	v_readlane_b32 s14, v254, 51
	v_readlane_b32 s15, v254, 52
	s_add_u32 s12, s14, s12
	s_addc_u32 s13, s15, s13
	s_bcnt1_i32_b64 s8, s[8:9]
	v_mov_b32_e32 v253, s8
	global_atomic_add v253, v1, v253, s[12:13] sc0

.LBB0_384:
	s_or_b64 exec, exec, s[4:5]
	v_lshl_add_u64 v[34:35], v[120:121], 1, s[2:3]
	s_waitcnt lgkmcnt(9)
	v_lshlrev_b64 v[46:47], 1, v[114:115]
	v_lshl_add_u64 v[34:35], v[34:35], 0, v[46:47]
	s_mov_b64 s[2:3], 0x3000000
	v_lshl_add_u64 v[36:37], v[34:35], 0, s[2:3]
	v_add_co_u32_e32 v34, vcc, 0x3000000, v34
	v_readlane_b32 s2, v255, 49
	s_nop 0
	v_addc_co_u32_e32 v35, vcc, 0, v35, vcc
	s_waitcnt lgkmcnt(7)
	s_nop 0
	v_lshl_add_u32 v0, s2, 11, v0
	s_waitcnt lgkmcnt(6)
	v_lshlrev_b64 v[52:53], 11, v[0:1]
	v_readlane_b32 s2, v255, 50
	v_lshl_add_u64 v[52:53], s[56:57], 0, v[52:53]
	s_lshl_b32 s80, s2, 7
	v_lshl_add_u64 v[52:53], v[52:53], 0, s[80:81]
	v_lshl_add_u64 v[46:47], v[52:53], 0, v[46:47]
	s_waitcnt lgkmcnt(0)
	s_barrier
	v_mov_b32_e32 v48, v192
	v_mov_b32_e32 v49, v193
	v_mov_b32_e32 v50, v194
	v_mov_b32_e32 v51, v195
	v_mov_b32_e32 v42, v218
	v_mov_b32_e32 v43, v219
	v_mov_b32_e32 v44, v220
	v_mov_b32_e32 v45, v221
	v_mov_b32_e32 v38, v222
	v_mov_b32_e32 v39, v223
	v_mov_b32_e32 v40, v224
	v_mov_b32_e32 v41, v225
	v_mov_b32_e32 v34, v240
	v_mov_b32_e32 v35, v241
	v_mov_b32_e32 v36, v242
	v_mov_b32_e32 v37, v243
	s_mov_b64 s[2:3], 0
	v_mov_b32_e32 v0, v50
	s_nop 1
	v_permlane32_swap_b32_e32 v48, v0
	v_lshlrev_b32_e32 v50, 16, v48
	s_waitcnt lgkmcnt(3)
	v_mov_b32_e32 v54, v51
	v_and_b32_e32 v51, 0xffff0000, v48
	v_mul_f32_e32 v48, 0xbfb8aa3b, v50
	v_exp_f32_e32 v48, v48
	v_permlane32_swap_b32_e32 v49, v54
	v_add_f32_e32 v48, 1.0, v48
	v_rcp_f32_e32 v52, v48
	v_mul_f32_e32 v48, 0xbfb8aa3b, v51
	v_exp_f32_e32 v48, v48
	s_nop 0
	v_add_f32_e32 v48, 1.0, v48
	v_rcp_f32_e32 v53, v48
	v_lshlrev_b32_e32 v48, 16, v49
	v_and_b32_e32 v49, 0xffff0000, v49
	v_mul_f32 v50, v52, v50
	v_mul_f32 v51, v53, v51
	s_nop 0
	v_mul_f32 v18, v18, v50
	v_mul_f32 v19, v19, v51
	s_nop 0
	v_cvt_pk_bf16_f32 v18, v18, v19
	v_mul_f32_e32 v19, 0xbfb8aa3b, v48
	v_exp_f32_e32 v19, v19
	s_nop 0
	v_add_f32_e32 v19, 1.0, v19
	v_rcp_f32_e32 v50, v19
	v_mul_f32_e32 v19, 0xbfb8aa3b, v49
	v_exp_f32_e32 v19, v19
	s_nop 0
	v_add_f32_e32 v19, 1.0, v19
	v_rcp_f32_e32 v51, v19
	s_nop 0
	v_mul_f32 v48, v50, v48
	v_mul_f32 v49, v51, v49
	s_nop 0
	v_mul_f32 v20, v20, v48
	v_mul_f32 v21, v21, v49
	s_nop 0
	v_cvt_pk_bf16_f32 v19, v20, v21
	v_lshlrev_b32_e32 v20, 16, v0
	v_and_b32_e32 v21, 0xffff0000, v0
	v_mul_f32_e32 v0, 0xbfb8aa3b, v20
	v_exp_f32_e32 v0, v0
	s_nop 0
	v_add_f32_e32 v0, 1.0, v0
	v_rcp_f32_e32 v48, v0
	v_mul_f32_e32 v0, 0xbfb8aa3b, v21
	v_exp_f32_e32 v0, v0
	s_nop 0
	v_add_f32_e32 v0, 1.0, v0
	v_rcp_f32_e32 v49, v0
	s_nop 0
	v_mul_f32 v20, v48, v20
	v_mul_f32 v21, v49, v21
	s_nop 0
	v_mul_f32 v20, v22, v20
	v_mul_f32 v21, v23, v21
	v_lshlrev_b32_e32 v22, 16, v54
	v_mul_f32_e32 v0, 0xbfb8aa3b, v22
	v_exp_f32_e32 v0, v0
	v_and_b32_e32 v23, 0xffff0000, v54
	v_cvt_pk_bf16_f32 v20, v20, v21
	s_nop 1
	v_permlane32_swap_b32_e32 v18, v20
	v_add_f32_e32 v0, 1.0, v0
	v_rcp_f32_e32 v48, v0
	v_mul_f32_e32 v0, 0xbfb8aa3b, v23
	v_exp_f32_e32 v0, v0
	s_nop 0
	v_add_f32_e32 v0, 1.0, v0
	v_rcp_f32_e32 v49, v0
	v_mov_b32_e32 v0, v44
	s_nop 1
	v_permlane32_swap_b32_e32 v42, v0
	v_mul_f32 v22, v48, v22
	v_mul_f32 v23, v49, v23
	s_nop 0
	v_mul_f32 v22, v24, v22
	v_mul_f32 v23, v25, v23
	s_nop 0
	v_cvt_pk_bf16_f32 v21, v22, v23
	s_nop 1
	v_permlane32_swap_b32_e32 v19, v21
	global_store_dwordx4 v[46:47], v[18:21], off
	v_mov_b32_e32 v22, v45
	s_nop 1
	v_permlane32_swap_b32_e32 v43, v22
	v_lshlrev_b32_e32 v18, 16, v42
	v_and_b32_e32 v19, 0xffff0000, v42
	v_mul_f32_e32 v20, 0xbfb8aa3b, v18
	v_mul_f32_e32 v21, 0xbfb8aa3b, v19
	v_exp_f32_e32 v20, v20
	v_exp_f32_e32 v21, v21
	v_add_f32_e32 v20, 1.0, v20
	v_add_f32_e32 v21, 1.0, v21
	v_rcp_f32_e32 v20, v20
	v_rcp_f32_e32 v21, v21
	s_nop 0
	v_mul_f32 v18, v20, v18
	v_mul_f32 v19, v21, v19
	s_nop 0
	v_mul_f32 v2, v2, v18
	v_mul_f32 v3, v3, v19
	v_lshlrev_b32_e32 v18, 16, v43
	v_cvt_pk_bf16_f32 v2, v2, v3
	v_mul_f32_e32 v3, 0xbfb8aa3b, v18
	v_exp_f32_e32 v3, v3
	v_and_b32_e32 v19, 0xffff0000, v43
	v_add_f32_e32 v3, 1.0, v3
	v_rcp_f32_e32 v20, v3
	v_mul_f32_e32 v3, 0xbfb8aa3b, v19
	v_exp_f32_e32 v3, v3
	s_nop 0
	v_add_f32_e32 v3, 1.0, v3
	v_rcp_f32_e32 v21, v3
	s_nop 0
	v_mul_f32 v18, v20, v18
	v_mul_f32 v19, v21, v19
	s_nop 0
	v_mul_f32 v4, v4, v18
	v_mul_f32 v5, v5, v19
	s_nop 0
	v_cvt_pk_bf16_f32 v3, v4, v5
	v_lshlrev_b32_e32 v4, 16, v0
	v_and_b32_e32 v5, 0xffff0000, v0
	v_mul_f32_e32 v0, 0xbfb8aa3b, v4
	v_exp_f32_e32 v0, v0
	s_nop 0
	v_add_f32_e32 v0, 1.0, v0
	v_rcp_f32_e32 v18, v0
	v_mul_f32_e32 v0, 0xbfb8aa3b, v5
	v_exp_f32_e32 v0, v0
	s_nop 0
	v_add_f32_e32 v0, 1.0, v0
	v_rcp_f32_e32 v19, v0
	s_nop 0
	v_mul_f32 v4, v18, v4
	v_mul_f32 v5, v19, v5
	s_nop 0
	v_mul_f32 v4, v6, v4
	v_mul_f32 v5, v7, v5
	v_lshlrev_b32_e32 v6, 16, v22
	v_mul_f32_e32 v0, 0xbfb8aa3b, v6
	v_exp_f32_e32 v0, v0
	v_and_b32_e32 v7, 0xffff0000, v22
	v_cvt_pk_bf16_f32 v4, v4, v5
	s_nop 1
	v_permlane32_swap_b32_e32 v2, v4
	v_add_f32_e32 v0, 1.0, v0
	v_rcp_f32_e32 v18, v0
	v_mul_f32_e32 v0, 0xbfb8aa3b, v7
	v_exp_f32_e32 v0, v0
	s_nop 0
	v_add_f32_e32 v0, 1.0, v0
	v_rcp_f32_e32 v19, v0
	v_mov_b32_e32 v0, v40
	s_nop 1
	v_permlane32_swap_b32_e32 v38, v0
	v_mul_f32 v6, v18, v6
	v_mul_f32 v7, v19, v7
	s_nop 0
	v_mul_f32 v6, v8, v6
	v_mul_f32 v7, v9, v7
	v_mov_b32_e32 v8, v41
	v_cvt_pk_bf16_f32 v5, v6, v7
	s_nop 1
	v_permlane32_swap_b32_e32 v3, v5
	global_store_dwordx4 v[46:47], v[2:5], off offset:64
	v_permlane32_swap_b32_e32 v39, v8
	s_nop 0
	v_lshlrev_b32_e32 v2, 16, v38
	v_and_b32_e32 v3, 0xffff0000, v38
	v_mul_f32_e32 v4, 0xbfb8aa3b, v2
	v_mul_f32_e32 v5, 0xbfb8aa3b, v3
	v_exp_f32_e32 v4, v4
	v_exp_f32_e32 v5, v5
	v_add_f32_e32 v4, 1.0, v4
	v_add_f32_e32 v5, 1.0, v5
	v_rcp_f32_e32 v4, v4
	v_rcp_f32_e32 v5, v5
	s_nop 0
	v_mul_f32 v2, v4, v2
	v_mul_f32 v3, v5, v3
	s_nop 0
	v_mul_f32 v2, v26, v2
	v_mul_f32 v3, v27, v3
	v_lshlrev_b32_e32 v4, 16, v39
	v_cvt_pk_bf16_f32 v2, v2, v3
	v_mul_f32_e32 v3, 0xbfb8aa3b, v4
	v_exp_f32_e32 v3, v3
	v_and_b32_e32 v5, 0xffff0000, v39
	v_add_f32_e32 v3, 1.0, v3
	v_rcp_f32_e32 v6, v3
	v_mul_f32_e32 v3, 0xbfb8aa3b, v5
	v_exp_f32_e32 v3, v3
	s_nop 0
	v_add_f32_e32 v3, 1.0, v3
	v_rcp_f32_e32 v7, v3
	s_nop 0
	v_mul_f32 v4, v6, v4
	v_mul_f32 v5, v7, v5
	s_nop 0
	v_mul_f32 v4, v28, v4
	v_mul_f32 v5, v29, v5
	s_nop 0
	v_cvt_pk_bf16_f32 v3, v4, v5
	v_lshlrev_b32_e32 v4, 16, v0
	v_and_b32_e32 v5, 0xffff0000, v0
	v_mul_f32_e32 v0, 0xbfb8aa3b, v4
	v_exp_f32_e32 v0, v0
	s_nop 0
	v_add_f32_e32 v0, 1.0, v0
	v_rcp_f32_e32 v6, v0
	v_mul_f32_e32 v0, 0xbfb8aa3b, v5
	v_exp_f32_e32 v0, v0
	s_nop 0
	v_add_f32_e32 v0, 1.0, v0
	v_rcp_f32_e32 v7, v0
	s_nop 0
	v_mul_f32 v4, v6, v4
	v_mul_f32 v5, v7, v5
	v_lshlrev_b32_e32 v6, 16, v8
	v_mul_f32_e32 v0, 0xbfb8aa3b, v6
	v_exp_f32_e32 v0, v0
	v_and_b32_e32 v7, 0xffff0000, v8
	v_mul_f32 v4, v30, v4
	v_mul_f32 v5, v31, v5
	v_add_f32_e32 v0, 1.0, v0
	v_rcp_f32_e32 v8, v0
	v_mul_f32_e32 v0, 0xbfb8aa3b, v7
	v_exp_f32_e32 v0, v0
	v_cvt_pk_bf16_f32 v4, v4, v5
	s_nop 1
	v_permlane32_swap_b32_e32 v2, v4
	v_add_f32_e32 v0, 1.0, v0
	v_rcp_f32_e32 v9, v0
	v_mov_b32_e32 v0, v36
	s_nop 1
	v_permlane32_swap_b32_e32 v34, v0
	v_mul_f32 v6, v8, v6
	v_mul_f32 v7, v9, v7
	v_mov_b32_e32 v8, v37
	v_mul_f32 v6, v32, v6
	v_mul_f32 v7, v33, v7
	s_nop 0
	v_permlane32_swap_b32_e32 v35, v8
	v_cvt_pk_bf16_f32 v5, v6, v7
	s_nop 1
	v_permlane32_swap_b32_e32 v3, v5
	global_store_dwordx4 v[46:47], v[2:5], off offset:32
	s_nop 1
	v_lshlrev_b32_e32 v2, 16, v34
	v_and_b32_e32 v3, 0xffff0000, v34
	v_mul_f32_e32 v4, 0xbfb8aa3b, v2
	v_mul_f32_e32 v5, 0xbfb8aa3b, v3
	v_exp_f32_e32 v4, v4
	v_exp_f32_e32 v5, v5
	v_add_f32_e32 v4, 1.0, v4
	v_add_f32_e32 v5, 1.0, v5
	v_rcp_f32_e32 v4, v4
	v_rcp_f32_e32 v5, v5
	s_nop 0
	v_mul_f32 v2, v4, v2
	v_mul_f32 v3, v5, v3
	s_nop 0
	v_mul_f32 v2, v10, v2
	v_mul_f32 v3, v11, v3
	v_lshlrev_b32_e32 v4, 16, v35
	v_cvt_pk_bf16_f32 v2, v2, v3
	v_mul_f32_e32 v3, 0xbfb8aa3b, v4
	v_exp_f32_e32 v3, v3
	v_and_b32_e32 v5, 0xffff0000, v35
	v_add_f32_e32 v3, 1.0, v3
	v_rcp_f32_e32 v6, v3
	v_mul_f32_e32 v3, 0xbfb8aa3b, v5
	v_exp_f32_e32 v3, v3
	s_nop 0
	v_add_f32_e32 v3, 1.0, v3
	v_rcp_f32_e32 v7, v3
	s_nop 0
	v_mul_f32 v4, v6, v4
	v_mul_f32 v5, v7, v5
	s_nop 0
	v_mul_f32 v4, v12, v4
	v_mul_f32 v5, v13, v5
	s_nop 0
	v_cvt_pk_bf16_f32 v3, v4, v5
	v_lshlrev_b32_e32 v4, 16, v0
	v_and_b32_e32 v5, 0xffff0000, v0
	v_mul_f32_e32 v0, 0xbfb8aa3b, v4
	v_exp_f32_e32 v0, v0
	s_nop 0
	v_add_f32_e32 v0, 1.0, v0
	v_rcp_f32_e32 v6, v0
	v_mul_f32_e32 v0, 0xbfb8aa3b, v5
	v_exp_f32_e32 v0, v0
	s_nop 0
	v_add_f32_e32 v0, 1.0, v0
	v_rcp_f32_e32 v7, v0
	s_nop 0
	v_mul_f32 v4, v6, v4
	v_mul_f32 v5, v7, v5
	v_lshlrev_b32_e32 v6, 16, v8
	v_mul_f32_e32 v0, 0xbfb8aa3b, v6
	v_exp_f32_e32 v0, v0
	v_and_b32_e32 v7, 0xffff0000, v8
	v_mul_f32 v4, v14, v4
	v_mul_f32 v5, v15, v5
	v_add_f32_e32 v0, 1.0, v0
	v_rcp_f32_e32 v8, v0
	v_mul_f32_e32 v0, 0xbfb8aa3b, v7
	v_exp_f32_e32 v0, v0
	v_cvt_pk_bf16_f32 v4, v4, v5
	s_nop 1
	v_permlane32_swap_b32_e32 v2, v4
	v_add_f32_e32 v0, 1.0, v0
	v_rcp_f32_e32 v9, v0
	s_nop 0
	v_mul_f32 v6, v8, v6
	v_mul_f32 v7, v9, v7
	s_nop 0
	v_mul_f32 v6, v16, v6
	v_mul_f32 v7, v17, v7
	s_nop 0
	v_cvt_pk_bf16_f32 v5, v6, v7
	s_nop 1
	v_permlane32_swap_b32_e32 v3, v5
	global_store_dwordx4 v[46:47], v[2:5], off offset:96
	s_waitcnt vmcnt(4)
	v_min_u32_e32 v253, 0xffff, v253
	v_or_b32_e32 v95, v95, v253
